# DF unit prologue: K/V staging issued right after Q arrives, before the q-norm bound is computed
# speedup vs baseline: 1.0045x; 1.0045x over previous
.LBB0_385:
	s_and_b64 vcc, exec, s[2:3]
	s_cbranch_vccz .LBB0_300
	s_lshr_b32 s2, s97, 4
	s_bfe_u32 s22, s97, 0x40001
	s_and_b32 s2, s2, 2
	s_and_b32 s3, s97, 1
	s_ashr_i32 s6, s97, 6
	s_xor_b32 s8, s22, 15
	s_or_b32 s2, s2, s3
	s_xor_b32 s16, s2, 2
	s_lshl_b32 s2, s8, 7
	v_readlane_b32 s3, v255, 29
	s_ashr_i32 s7, s6, 31
	s_or_b32 s9, s2, s3
	s_lshl_b32 s10, s16, 18
	s_lshl_b64 s[2:3], s[6:7], 21
	v_mov_b32_e32 v216, v231
	s_add_u32 s17, s78, s2
	s_addc_u32 s18, s79, s3
	v_and_b32_e32 v218, 31, v216
	s_lshl_b32 s2, s16, 19
	v_or_b32_e32 v179, s9, v218
	s_add_u32 s2, s17, s2
	s_addc_u32 s3, s18, 0
	v_lshlrev_b32_e32 v0, 8, v179
	v_ashrrev_i32_e32 v219, 5, v216
	v_lshl_add_u64 v[2:3], s[2:3], 0, v[0:1]
	s_mov_b32 s85, s81
	v_lshl_add_u64 v[4:5], v[2:3], 0, s[84:85]
	v_lshlrev_b32_e32 v2, 3, v219
	v_ashrrev_i32_e32 v3, 31, v2
	v_lshl_add_u64 v[4:5], v[2:3], 1, v[4:5]
	s_brev_b32 s2, 32
	v_add_co_u32_e32 v6, vcc, s2, v4
	s_mov_b64 s[2:3], 0x4000000
	s_nop 0
	v_addc_co_u32_e32 v7, vcc, 0, v5, vcc
	global_load_dwordx4 v[112:115], v[6:7], off
	v_lshl_add_u64 v[4:5], v[4:5], 0, s[2:3]
	global_load_dwordx4 v[116:119], v[4:5], off offset:32
	global_load_dwordx4 v[120:123], v[4:5], off offset:64
	global_load_dwordx4 v[124:127], v[4:5], off offset:96
	s_lshl_b32 s2, s6, 5
	s_lshl_b32 s3, s16, 3
	v_readlane_b32 s4, v255, 26
	s_add_i32 s2, s2, 0
	s_lshl_b32 s4, s4, 2
	s_add_i32 s2, s2, s3
	s_add_i32 s2, s2, s4
	s_add_i32 s2, s2, 0x24a00
	v_mov_b32_e32 v0, s2
	ds_read_b32 v3, v0
	s_waitcnt vmcnt(0)
	v_lshlrev_b32_e32 v0, 3, v216
	v_cmp_gt_i32_e32 vcc, 2, v216
	s_and_saveexec_b64 s[2:3], vcc
	v_add_u32_e32 v3, s68, v0
	ds_write_b8 v3, v1
	s_or_b64 exec, exec, s[2:3]
	v_ashrrev_i32_e32 v3, 3, v216
	v_readlane_b32 s2, v255, 11
	v_and_b32_e32 v8, 24, v0
	s_lshl_b32 s19, s10, 1
	v_add_u32_e32 v3, s2, v3
	v_readlane_b32 s2, v255, 12
	v_lshrrev_b32_e32 v4, 1, v3
	v_add_u32_e32 v2, s30, v2
	v_or_b32_e32 v9, s2, v8
	v_lshrrev_b32_e32 v7, 2, v216
	v_lshlrev_b32_e32 v0, 1, v216
	v_lshlrev_b32_e32 v178, 2, v219
	s_lshl_b32 s23, s8, 1
	v_xor_b32_e32 v6, v4, v216
	v_and_or_b32 v4, v7, 7, v2
	v_lshlrev_b32_e32 v2, 7, v3
	v_and_b32_e32 v10, 32, v0
	v_and_or_b32 v0, v7, 3, v178
	s_add_u32 s2, s17, s19
	v_ashrrev_i32_e32 v3, 31, v2
	v_lshlrev_b32_e32 v7, 6, v0
	s_addc_u32 s3, s18, 0
	v_lshlrev_b32_e32 v0, 4, v6
	v_lshlrev_b32_e32 v4, 7, v4
	v_lshl_add_u64 v[2:3], v[2:3], 1, s[2:3]
	v_and_b32_e32 v0, 0x70, v0
	v_ashrrev_i32_e32 v5, 31, v4
	v_lshl_add_u64 v[2:3], v[2:3], 0, v[0:1]
	s_mov_b64 s[10:11], 0x5000000
	v_lshl_add_u64 v[180:181], v[2:3], 0, s[10:11]
	v_lshl_add_u64 v[2:3], v[4:5], 1, s[2:3]
	v_lshlrev_b32_e32 v0, 1, v9
	v_lshl_add_u64 v[2:3], v[2:3], 0, v[0:1]
	s_mov_b64 s[2:3], 0x6000000
	v_lshl_add_u64 v[182:183], v[2:3], 0, s[2:3]
	s_lshl_b32 s2, s8, 15
	s_lshr_b32 s21, s9, 6
	s_or_b32 s80, s2, 0x4000
	s_mov_b32 s3, s81
	v_lshl_add_u64 v[200:201], v[180:181], 0, s[80:81]
	v_lshl_add_u64 v[194:195], v[182:183], 0, s[80:81]
	v_lshl_add_u64 v[190:191], v[180:181], 0, s[2:3]
	v_lshl_add_u64 v[184:185], v[182:183], 0, s[2:3]
	v_or3_b32 v220, v7, v10, v8
	v_lshl_add_u64 v[198:199], v[200:201], 0, s[88:89]
	v_lshl_add_u64 v[192:193], v[194:195], 0, s[88:89]
	v_lshl_add_u64 v[188:189], v[190:191], 0, s[88:89]
	v_lshl_add_u64 v[186:187], v[184:185], 0, s[88:89]
	s_mov_b32 s2, m0
	s_mov_b32 m0, s76
	s_nop 0
	global_load_lds_dwordx4 v[200:201], off
	s_mov_b32 m0, s2
	v_readlane_b32 s3, v255, 15
	s_mov_b32 s2, m0
	s_mov_b32 m0, s3
	s_nop 0
	global_load_lds_dwordx4 v[198:199], off
	s_mov_b32 m0, s2
	v_readlane_b32 s3, v255, 16
	s_mov_b32 s2, m0
	s_mov_b32 m0, s31
	s_nop 0
	global_load_lds_dwordx4 v[194:195], off
	s_mov_b32 m0, s2
	s_cmp_eq_u32 s22, 15
	s_mov_b32 s2, m0
	s_mov_b32 m0, s3
	s_nop 0
	global_load_lds_dwordx4 v[192:193], off
	s_mov_b32 m0, s2
	v_readlane_b32 s3, v255, 17
	s_mov_b32 s2, m0
	s_mov_b32 m0, s3
	s_nop 0
	global_load_lds_dwordx4 v[190:191], off
	s_mov_b32 m0, s2
	v_readlane_b32 s3, v255, 18
	s_mov_b32 s2, m0
	s_mov_b32 m0, s3
	s_nop 0
	global_load_lds_dwordx4 v[188:189], off
	s_mov_b32 m0, s2
	v_readlane_b32 s3, v255, 19
	s_mov_b32 s2, m0
	s_mov_b32 m0, s3
	s_nop 0
	global_load_lds_dwordx4 v[184:185], off
	s_mov_b32 m0, s2
	v_readlane_b32 s3, v255, 20
	s_mov_b32 s2, m0
	s_mov_b32 m0, s3
	s_nop 0
	global_load_lds_dwordx4 v[186:187], off
	s_mov_b32 m0, s2
	s_cbranch_scc1 .Ldfs_skip3
	s_add_i32 s80, s23, -1
	s_lshl_b64 s[2:3], s[80:81], 14
	v_lshl_add_u64 v[2:3], v[180:181], 0, s[2:3]
	v_readlane_b32 s8, v255, 21
	s_mov_b32 s5, m0
	s_mov_b32 m0, s8
	s_nop 0
	global_load_lds_dwordx4 v[2:3], off
	s_mov_b32 m0, s5
	v_lshl_add_u64 v[2:3], v[2:3], 0, s[88:89]
	v_readlane_b32 s8, v255, 22
	s_mov_b32 s5, m0
	s_mov_b32 m0, s8
	s_nop 0
	global_load_lds_dwordx4 v[2:3], off
	s_mov_b32 m0, s5
	v_lshl_add_u64 v[2:3], v[182:183], 0, s[2:3]
	v_readlane_b32 s3, v255, 23
	s_mov_b32 s2, m0
	s_mov_b32 m0, s3
	s_nop 0
	global_load_lds_dwordx4 v[2:3], off
	s_mov_b32 m0, s2
	v_lshl_add_u64 v[2:3], v[2:3], 0, s[88:89]
	v_readlane_b32 s3, v255, 24
	s_mov_b32 s2, m0
	s_mov_b32 m0, s3
	s_nop 0
	global_load_lds_dwordx4 v[2:3], off
	s_mov_b32 m0, s2
.Ldfs_skip3:
	v_lshlrev_b32_e32 v11, 16, v116
	v_lshlrev_b32_e32 v0, 16, v112
	v_and_b32_e32 v4, 0xffff0000, v112
	v_fma_f32 v0, v0, v0, 0
	v_lshlrev_b32_e32 v5, 16, v113
	v_fmac_f32_e32 v0, v4, v4
	v_and_b32_e32 v6, 0xffff0000, v113
	v_fmac_f32_e32 v0, v5, v5
	v_lshlrev_b32_e32 v7, 16, v114
	v_fmac_f32_e32 v0, v6, v6
	v_and_b32_e32 v8, 0xffff0000, v114
	v_fmac_f32_e32 v0, v7, v7
	v_lshlrev_b32_e32 v9, 16, v115
	v_fmac_f32_e32 v0, v8, v8
	v_and_b32_e32 v10, 0xffff0000, v115
	v_fmac_f32_e32 v0, v9, v9
	v_fmac_f32_e32 v0, v10, v10
	v_and_b32_e32 v12, 0xffff0000, v116
	v_fmac_f32_e32 v0, v11, v11
	v_lshlrev_b32_e32 v13, 16, v117
	v_fmac_f32_e32 v0, v12, v12
	v_and_b32_e32 v14, 0xffff0000, v117
	v_fmac_f32_e32 v0, v13, v13
	v_lshlrev_b32_e32 v15, 16, v118
	v_fmac_f32_e32 v0, v14, v14
	v_and_b32_e32 v16, 0xffff0000, v118
	v_fmac_f32_e32 v0, v15, v15
	v_lshlrev_b32_e32 v17, 16, v119
	v_fmac_f32_e32 v0, v16, v16
	v_and_b32_e32 v18, 0xffff0000, v119
	v_fmac_f32_e32 v0, v17, v17
	v_lshlrev_b32_e32 v19, 16, v120
	v_fmac_f32_e32 v0, v18, v18
	v_and_b32_e32 v20, 0xffff0000, v120
	v_fmac_f32_e32 v0, v19, v19
	v_lshlrev_b32_e32 v21, 16, v121
	v_fmac_f32_e32 v0, v20, v20
	v_and_b32_e32 v22, 0xffff0000, v121
	v_fmac_f32_e32 v0, v21, v21
	v_lshlrev_b32_e32 v23, 16, v122
	v_fmac_f32_e32 v0, v22, v22
	v_and_b32_e32 v24, 0xffff0000, v122
	v_fmac_f32_e32 v0, v23, v23
	v_lshlrev_b32_e32 v25, 16, v123
	v_fmac_f32_e32 v0, v24, v24
	v_and_b32_e32 v26, 0xffff0000, v123
	v_fmac_f32_e32 v0, v25, v25
	v_lshlrev_b32_e32 v27, 16, v124
	v_fmac_f32_e32 v0, v26, v26
	v_and_b32_e32 v28, 0xffff0000, v124
	v_fmac_f32_e32 v0, v27, v27
	v_lshlrev_b32_e32 v29, 16, v125
	v_fmac_f32_e32 v0, v28, v28
	v_and_b32_e32 v30, 0xffff0000, v125
	v_fmac_f32_e32 v0, v29, v29
	v_lshlrev_b32_e32 v31, 16, v126
	v_fmac_f32_e32 v0, v30, v30
	v_and_b32_e32 v32, 0xffff0000, v126
	v_fmac_f32_e32 v0, v31, v31
	v_lshlrev_b32_e32 v33, 16, v127
	v_fmac_f32_e32 v0, v32, v32
	v_and_b32_e32 v34, 0xffff0000, v127
	v_fmac_f32_e32 v0, v33, v33
	v_fmac_f32_e32 v0, v34, v34
	v_mov_b32_e32 v4, v0
	s_nop 1
	v_permlane32_swap_b32_e32 v0, v4
	v_add_f32_e32 v0, v0, v4
	s_nop 1
	v_mov_b32_dpp v4, v0 row_shr:1 row_mask:0xf bank_mask:0xf bound_ctrl:1
	v_max_f32_e32 v4, v4, v4
	v_max_f32_e32 v0, v0, v4
	s_nop 1
	v_mov_b32_dpp v4, v0 row_shr:2 row_mask:0xf bank_mask:0xf bound_ctrl:1
	v_max_f32_e32 v4, v4, v4
	v_max_f32_e32 v0, v0, v4
	s_nop 1
	v_mov_b32_dpp v4, v0 row_shr:4 row_mask:0xf bank_mask:0xf bound_ctrl:1
	v_max_f32_e32 v4, v4, v4
	v_max_f32_e32 v0, v0, v4
	s_nop 1
	v_mov_b32_dpp v4, v0 row_shr:8 row_mask:0xf bank_mask:0xf bound_ctrl:1
	v_max_f32_e32 v4, v4, v4
	v_max_f32_e32 v0, v0, v4
	v_mov_b32_e32 v4, v0
	s_nop 1
	v_permlane16_swap_b32_e32 v0, v4
	v_max_f32_e32 v4, v4, v4
	v_max_f32_e32 v0, v0, v0
	v_max_f32_e32 v0, v0, v4
	s_nop 0
	v_readlane_b32 s2, v0, 15
	s_waitcnt lgkmcnt(0)
	s_nop 0
	v_mul_f32_e32 v0, s2, v3
	s_mov_b32 s2, 0xf800000
	v_mul_f32_e32 v4, 0x4f800000, v0
	v_cmp_gt_f32_e32 vcc, s2, v0
	s_nop 1
	v_cndmask_b32_e32 v4, v0, v4, vcc
	v_sqrt_f32_e32 v5, v4
	v_lshlrev_b32_e32 v0, 3, v216
	v_add_u32_e32 v6, -1, v5
	v_add_u32_e32 v7, 1, v5
	v_fma_f32 v8, -v6, v5, v4
	v_fma_f32 v9, -v7, v5, v4
	v_cmp_ge_f32_e64 s[4:5], 0, v8
	s_nop 1
	v_cndmask_b32_e64 v5, v5, v6, s[4:5]
	v_cmp_lt_f32_e64 s[4:5], 0, v9
	s_nop 1
	v_cndmask_b32_e64 v5, v5, v7, s[4:5]
	v_mul_f32_e32 v6, 0x37800000, v5
	v_cndmask_b32_e32 v5, v5, v6, vcc
	v_cmp_class_f32_e32 vcc, v4, v232
	s_nop 1
	v_cndmask_b32_e32 v4, v5, v4, vcc
	v_mul_f32_e32 v4, 0x3e38aa3b, v4
	v_cmp_lt_f32_e32 vcc, 0, v3
	v_mov_b32_e32 v3, 0x7f800000
	s_nop 0
	v_cndmask_b32_e32 v3, v3, v4, vcc
	v_cmp_gt_i32_e32 vcc, 2, v216
	v_readfirstlane_b32 s20, v3
	s_lshl_b32 s2, s16, 24
	s_sub_i32 s4, -2.0, s2
	v_readlane_b32 s8, v255, 13
	v_readlane_b32 s9, v255, 14
	s_mov_b64 s[2:3], -1
	s_andn2_b64 vcc, exec, s[8:9]
	s_cbranch_vccnz .LBB0_424
	s_mov_b32 s2, m0
	s_mov_b32 m0, s76
	s_nop 0
	s_mov_b32 m0, s2
	v_readlane_b32 s3, v255, 15
	s_mov_b32 s2, m0
	s_mov_b32 m0, s3
	s_nop 0
	s_mov_b32 m0, s2
	v_readlane_b32 s3, v255, 16
	s_mov_b32 s2, m0
	s_mov_b32 m0, s31
	s_nop 0
	s_mov_b32 m0, s2
	s_cmp_eq_u32 s22, 15
	s_mov_b32 s2, m0
	s_mov_b32 m0, s3
	s_nop 0
	s_mov_b32 m0, s2
	v_readlane_b32 s3, v255, 17
	s_mov_b32 s2, m0
	s_mov_b32 m0, s3
	s_nop 0
	s_mov_b32 m0, s2
	v_readlane_b32 s3, v255, 18
	s_mov_b32 s2, m0
	s_mov_b32 m0, s3
	s_nop 0
	s_mov_b32 m0, s2
	v_readlane_b32 s3, v255, 19
	s_mov_b32 s2, m0
	s_mov_b32 m0, s3
	s_nop 0
	s_mov_b32 m0, s2
	v_readlane_b32 s3, v255, 20
	s_mov_b32 s2, m0
	s_mov_b32 m0, s3
	s_nop 0
	s_mov_b32 m0, s2
	s_cbranch_scc1 .LBB0_391
	s_add_i32 s80, s23, -1
	s_lshl_b64 s[2:3], s[80:81], 14
	v_lshl_add_u64 v[2:3], v[180:181], 0, s[2:3]
	v_readlane_b32 s8, v255, 21
	s_mov_b32 s5, m0
	s_mov_b32 m0, s8
	s_nop 0
	s_mov_b32 m0, s5
	v_lshl_add_u64 v[2:3], v[2:3], 0, s[88:89]
	v_readlane_b32 s8, v255, 22
	s_mov_b32 s5, m0
	s_mov_b32 m0, s8
	s_nop 0
	s_mov_b32 m0, s5
	v_lshl_add_u64 v[2:3], v[182:183], 0, s[2:3]
	v_readlane_b32 s3, v255, 23
	s_mov_b32 s2, m0
	s_mov_b32 m0, s3
	s_nop 0
	s_mov_b32 m0, s2
	v_lshl_add_u64 v[2:3], v[2:3], 0, s[88:89]
	v_readlane_b32 s3, v255, 24
	s_mov_b32 s2, m0
	s_mov_b32 m0, s3
	s_nop 0
	s_mov_b32 m0, s2

.LBB0_424:
	s_and_b64 vcc, exec, s[2:3]
	s_cbranch_vccz .LBB0_451
	s_mov_b32 s2, m0
	s_mov_b32 m0, s76
	s_nop 0
	s_mov_b32 m0, s2
	v_readlane_b32 s3, v255, 15
	s_mov_b32 s2, m0
	s_mov_b32 m0, s3
	s_nop 0
	s_mov_b32 m0, s2
	v_readlane_b32 s3, v255, 16
	s_mov_b32 s2, m0
	s_mov_b32 m0, s31
	s_nop 0
	s_mov_b32 m0, s2
	s_cmp_eq_u32 s22, 15
	s_mov_b32 s2, m0
	s_mov_b32 m0, s3
	s_nop 0
	s_mov_b32 m0, s2
	v_readlane_b32 s3, v255, 17
	s_mov_b32 s2, m0
	s_mov_b32 m0, s3
	s_nop 0
	s_mov_b32 m0, s2
	v_readlane_b32 s3, v255, 18
	s_mov_b32 s2, m0
	s_mov_b32 m0, s3
	s_nop 0
	s_mov_b32 m0, s2
	v_readlane_b32 s3, v255, 19
	s_mov_b32 s2, m0
	s_mov_b32 m0, s3
	s_nop 0
	s_mov_b32 m0, s2
	v_readlane_b32 s3, v255, 20
	s_mov_b32 s2, m0
	s_mov_b32 m0, s3
	s_nop 0
	s_mov_b32 m0, s2
	s_cbranch_scc1 .LBB0_427
	s_add_i32 s80, s23, -1
	s_lshl_b64 s[2:3], s[80:81], 14
	v_lshl_add_u64 v[2:3], v[180:181], 0, s[2:3]
	v_readlane_b32 s8, v255, 21
	s_mov_b32 s5, m0
	s_mov_b32 m0, s8
	s_nop 0
	s_mov_b32 m0, s5
	v_lshl_add_u64 v[2:3], v[2:3], 0, s[88:89]
	v_readlane_b32 s8, v255, 22
	s_mov_b32 s5, m0
	s_mov_b32 m0, s8
	s_nop 0
	s_mov_b32 m0, s5
	v_lshl_add_u64 v[2:3], v[182:183], 0, s[2:3]
	v_readlane_b32 s3, v255, 23
	s_mov_b32 s2, m0
	s_mov_b32 m0, s3
	s_nop 0
	s_mov_b32 m0, s2
	v_lshl_add_u64 v[2:3], v[2:3], 0, s[88:89]
	v_readlane_b32 s3, v255, 24
	s_mov_b32 s2, m0
	s_mov_b32 m0, s3
	s_nop 0
	s_mov_b32 m0, s2
